# one static s_setprio 1 for waves 0-3 (the other half) from the first GEMM phase on
# baseline (speedup 1.0000x reference)
; template <class Epi, class Sched, bool ALIGN_EPI = false, bool SP2 = false>
; __device__ __forceinline__ void gemm_phase(PG8_LAS unsigned char* lds, const Gemm g, const Sched& S, const Epi& E) {
;     const int tid = threadIdx.x, wid = __builtin_amdgcn_readfirstlane(tid >> 6), lane = tid & 63, wr = wid >> 2, wc = wid & 3, fr = lane & 15, fq = lane >> 4;
.LBB0_196:
	v_readlane_b32 s98, v249, 18
	s_nop 3
	s_cmp_lt_u32 s98, 4
	s_cbranch_scc0 .Lprio_done
	s_setprio 1
